# selection loop: next pair's V loads issued one iteration ahead inside the PV fp8 MFMA shadow (software-pipelined V prefetch)
# baseline (speedup 1.0000x reference)
; __device__ __forceinline__ void nsa_unit(const Params& p, int bg, int jq, LAS unsigned char* lds, int wave, int lane, bool build_lut) {
;     ...
;             for (int it = 0; it < npair; ++it) {
;                 const int nb[2] = {n0, n1};
;                 const bool real1 = (2 * it + 1) < cnt;
; #pragma unroll
;                 for (int u = 0; u < 2; ++u)
; #pragma unroll
;                     for (int i = 0; i < 4; ++i) { const l64x2 t = *(const l64x2*)(vs8 + (size_t)nb[u] * 4096 + i * 1024 + lane * 16); v8[u][2 * i] = t[0]; v8[u][2 * i + 1] = t[1]; }
;                 bool ok[2];
;                 ok[0] = (selw[(grp * 4 + q4) * 8 + (nb[0] >> 5)] >> (nb[0] & 31)) & 1u;
;                 ok[1] = real1 && ((selw[(grp * 4 + q4) * 8 + (nb[1] >> 5)] >> (nb[1] & 31)) & 1u);
;                 const int bmax = real1 ? max(nb[0], nb[1]) : nb[0];
.LBB0_1200:
	v_mov_b32_e32 v238, s43
	ds_read_b64 v[238:239], v238
	s_ashr_i32 s6, s22, 5
	v_lshl_add_u32 v1, s6, 2, v167
	ds_read_b32 v1, v1 offset:8192
	s_ashr_i32 s6, s8, 5
	v_lshl_add_u32 v2, s6, 2, v167
	ds_read_b32 v240, v2 offset:8192
	s_cmp_lg_u32 s44, 0
	s_cbranch_scc1 .Lsel_skipv
	s_ashr_i32 s23, s22, 31
	s_lshl_b64 s[4:5], s[22:23], 12
	s_ashr_i32 s9, s8, 31
	v_lshl_add_u64 v[2:3], v[150:151], 0, s[4:5]
	s_lshl_b64 s[4:5], s[8:9], 12
	global_load_dwordx4 v[84:87], v[2:3], off
	global_load_dwordx4 v[80:83], v[2:3], off offset:1024
	global_load_dwordx4 v[76:79], v[2:3], off offset:2048
	global_load_dwordx4 v[72:75], v[2:3], off offset:3072
	v_lshl_add_u64 v[2:3], v[150:151], 0, s[4:5]
	global_load_dwordx4 v[68:71], v[2:3], off
	global_load_dwordx4 v[64:67], v[2:3], off offset:1024
	global_load_dwordx4 v[60:63], v[2:3], off offset:2048
	global_load_dwordx4 v[56:59], v[2:3], off offset:3072
.Lsel_skipv:
	s_cmp_lt_u32 s40, s38
	s_cselect_b64 s[4:5], -1, 0
	s_waitcnt lgkmcnt(0)
	v_lshrrev_b32_e32 v2, s8, v240
	v_and_b32_e32 v2, 1, v2
	v_cmp_eq_u32_e32 vcc, 1, v2
	s_and_b64 s[20:21], vcc, s[4:5]

; __device__ __forceinline__ void nsa_unit(const Params& p, int bg, int jq, LAS unsigned char* lds, int wave, int lane, bool build_lut) {
;     ...
;                 for (int u = 0; u < 2; ++u)
; #pragma unroll
;                     for (int i = 0; i < 4; ++i) { const l64x2 t = *(const l64x2*)(vs8 + (size_t)nb[u] * 4096 + i * 1024 + lane * 16); v8[u][2 * i] = t[0]; v8[u][2 * i + 1] = t[1]; }
;     ...
; #pragma unroll
;                 for (int u = 0; u < 2; ++u) {
;                     const long pb0 = pack_fp8x8(sc[u][0][0], sc[u][0][1], sc[u][0][2], sc[u][0][3], sc[u][1][0], sc[u][1][1], sc[u][1][2], sc[u][1][3]);
;                     const long pb1 = pack_fp8x8(sc[u][2][0], sc[u][2][1], sc[u][2][2], sc[u][2][3], sc[u][3][0], sc[u][3][1], sc[u][3][2], sc[u][3][3]);
; #pragma unroll
;                     for (int dt = 0; dt < 4; ++dt) {
;                         o[dt] = __builtin_amdgcn_mfma_f32_16x16x32_fp8_fp8(v8[u][2 * dt], pb0, o[dt], 0, 0, 0);
;                         o[dt] = __builtin_amdgcn_mfma_f32_16x16x32_fp8_fp8(v8[u][2 * dt + 1], pb1, o[dt], 0, 0, 0);
;                     }
;                     lacc = __builtin_amdgcn_mfma_f32_16x16x32_fp8_fp8(ones8, pb0, lacc, 0, 0, 0);
;                     lacc = __builtin_amdgcn_mfma_f32_16x16x32_fp8_fp8(ones8, pb1, lacc, 0, 0, 0);
;                 }
.Lsel_fast_exp:
	v_exp_f32_e32 v116, v116
	v_exp_f32_e32 v117, v117
	v_exp_f32_e32 v118, v118
	v_exp_f32_e32 v119, v119
	v_exp_f32_e32 v108, v108
	v_exp_f32_e32 v109, v109
	v_exp_f32_e32 v110, v110
	v_exp_f32_e32 v111, v111
	v_exp_f32_e32 v96, v96
	v_exp_f32_e32 v97, v97
	v_exp_f32_e32 v98, v98
	v_exp_f32_e32 v99, v99
	v_exp_f32_e32 v100, v100
	v_exp_f32_e32 v101, v101
	v_exp_f32_e32 v102, v102
	v_exp_f32_e32 v103, v103
	v_cvt_pk_fp8_f32 v244, v116, v117
	v_cvt_pk_fp8_f32 v245, v108, v109
	v_cvt_pk_fp8_f32 v246, v96, v97
	v_cvt_pk_fp8_f32 v247, v100, v101
	v_cvt_pk_fp8_f32 v244, v118, v119 op_sel:[0,0,1]
	v_cvt_pk_fp8_f32 v245, v110, v111 op_sel:[0,0,1]
	v_cvt_pk_fp8_f32 v246, v98, v99 op_sel:[0,0,1]
	v_cvt_pk_fp8_f32 v247, v102, v103 op_sel:[0,0,1]
	s_add_i32 s43, s43, 8
	s_add_i32 s40, s40, 2
	s_cmp_ge_u32 s44, s41
	s_cbranch_scc1 .Lsel_fast_pv_last
	s_lshl_b64 s[46:47], s[16:17], 12
	v_lshl_add_u64 v[2:3], v[150:151], 0, s[46:47]
	s_lshl_b64 s[46:47], s[18:19], 12
	v_lshl_add_u64 v[120:121], v[150:151], 0, s[46:47]
	s_waitcnt vmcnt(15)
	v_mfma_f32_16x16x32_fp8_fp8 v[48:51], v[84:85], v[244:245], v[48:51]
	v_exp_f32_e32 v112, v112
	v_exp_f32_e32 v113, v113
	v_mfma_f32_16x16x32_fp8_fp8 v[52:55], v[242:243], v[244:245], v[52:55]
	v_exp_f32_e32 v114, v114
	v_exp_f32_e32 v115, v115
	s_waitcnt vmcnt(14)
	v_mfma_f32_16x16x32_fp8_fp8 v[44:47], v[80:81], v[244:245], v[44:47]
	v_exp_f32_e32 v104, v104
	v_exp_f32_e32 v105, v105
	s_waitcnt vmcnt(13)
	v_mfma_f32_16x16x32_fp8_fp8 v[40:43], v[76:77], v[244:245], v[40:43]
	v_exp_f32_e32 v106, v106
	v_exp_f32_e32 v107, v107
	s_waitcnt vmcnt(12)
	v_mfma_f32_16x16x32_fp8_fp8 v[24:27], v[72:73], v[244:245], v[24:27]
	v_exp_f32_e32 v92, v92
	v_exp_f32_e32 v93, v93
	v_mfma_f32_16x16x32_fp8_fp8 v[48:51], v[86:87], v[246:247], v[48:51]
	global_load_dwordx4 v[84:87], v[2:3], off
	v_exp_f32_e32 v94, v94
	v_exp_f32_e32 v95, v95
	v_mfma_f32_16x16x32_fp8_fp8 v[44:47], v[82:83], v[246:247], v[44:47]
	global_load_dwordx4 v[80:83], v[2:3], off offset:1024
	v_exp_f32_e32 v88, v88
	v_exp_f32_e32 v89, v89
	v_mfma_f32_16x16x32_fp8_fp8 v[40:43], v[78:79], v[246:247], v[40:43]
	global_load_dwordx4 v[76:79], v[2:3], off offset:2048
	v_exp_f32_e32 v90, v90
	v_exp_f32_e32 v91, v91
	v_mfma_f32_16x16x32_fp8_fp8 v[24:27], v[74:75], v[246:247], v[24:27]
	global_load_dwordx4 v[72:75], v[2:3], off offset:3072
	v_cvt_pk_fp8_f32 v248, v112, v113
	v_cvt_pk_fp8_f32 v249, v104, v105
	v_mfma_f32_16x16x32_fp8_fp8 v[52:55], v[242:243], v[246:247], v[52:55]
	v_cvt_pk_fp8_f32 v248, v114, v115 op_sel:[0,0,1]
	v_cvt_pk_fp8_f32 v249, v106, v107 op_sel:[0,0,1]
	v_cvt_pk_fp8_f32 v250, v92, v93
	v_cvt_pk_fp8_f32 v251, v88, v89
	v_cvt_pk_fp8_f32 v250, v94, v95 op_sel:[0,0,1]
	v_cvt_pk_fp8_f32 v251, v90, v91 op_sel:[0,0,1]
	s_waitcnt vmcnt(15)
	v_mfma_f32_16x16x32_fp8_fp8 v[48:51], v[68:69], v[248:249], v[48:51]
	v_mfma_f32_16x16x32_fp8_fp8 v[52:55], v[242:243], v[248:249], v[52:55]
	s_waitcnt vmcnt(14)
	v_mfma_f32_16x16x32_fp8_fp8 v[44:47], v[64:65], v[248:249], v[44:47]
	s_waitcnt vmcnt(13)
	v_mfma_f32_16x16x32_fp8_fp8 v[40:43], v[60:61], v[248:249], v[40:43]
	s_waitcnt vmcnt(12)
	v_mfma_f32_16x16x32_fp8_fp8 v[24:27], v[56:57], v[248:249], v[24:27]
	v_mfma_f32_16x16x32_fp8_fp8 v[48:51], v[70:71], v[250:251], v[48:51]
	global_load_dwordx4 v[68:71], v[120:121], off
	v_mfma_f32_16x16x32_fp8_fp8 v[44:47], v[66:67], v[250:251], v[44:47]
	global_load_dwordx4 v[64:67], v[120:121], off offset:1024
	v_mfma_f32_16x16x32_fp8_fp8 v[40:43], v[62:63], v[250:251], v[40:43]
	global_load_dwordx4 v[60:63], v[120:121], off offset:2048
	v_mfma_f32_16x16x32_fp8_fp8 v[24:27], v[58:59], v[250:251], v[24:27]
	global_load_dwordx4 v[56:59], v[120:121], off offset:3072
	v_mfma_f32_16x16x32_fp8_fp8 v[52:55], v[242:243], v[250:251], v[52:55]
	s_mov_b32 s8, s18
	s_mov_b32 s22, s16
	s_branch .LBB0_1200
